# GU/in-proj loops: B-fragment ds_reads from one per-unit base VGPR with immediate offsets (load segments VALU-free)
# speedup vs baseline: 1.0040x; 1.0040x over previous
;     __device__ __forceinline__ void stage_rs(const Unit& u, int tid, int wid) const { stage_rs_lds(SS, rsl, u, tid, wid); }
;     __device__ __forceinline__ void stage_rs(const Unit& u, int tid, int wid) const { stage_rs_lds(SS, rsl, u, tid, wid); }
; #define PG8_STAGE(bufoff, gbase, voff) do { _Pragma("unroll") for (int _i = 0; _i < 2; ++_i) \
;         __builtin_amdgcn_global_load_lds((const unsigned*)((const char*)(gbase) + (voff)[_i]), (PG8_LAS unsigned*)(lds + (bufoff) + ldsw + _i * 8192), 16, 0, 0); } while (0)
; #define PG8_LDA(dst, b, h) do { _Pragma("unroll") for (int m = 0; m < 4; ++m) _Pragma("unroll") for (int k = 0; k < 2; ++k) dst[m][k] = *(const PG8_LAS bf16x8*)(lds + PG8_SA(b, h) + aoff + m * 2048 + k * 1024); } while (0)
; #define PG8_LDB(dst, b, h) do { _Pragma("unroll") for (int n = 0; n < 2; ++n) _Pragma("unroll") for (int k = 0; k < 2; ++k) dst[n][k] = *(const PG8_LAS bf16x8*)(lds + PG8_SB(b, h) + boff + n * 2048 + k * 1024); } while (0)
; #define PG8_BAR __builtin_amdgcn_s_barrier()
; template <class Epi, class Sched, bool ALIGN_EPI = false, bool SP2 = false>
; __device__ __forceinline__ void gemm_phase(PG8_LAS unsigned char* lds, const Gemm g, const Sched& S, const Epi& E, const int tid) {
;     ...
;             const bool last = (t == nt - 2);
;             if constexpr (Epi::RS_LDS) { if (t == nt - 4) E.stage_rs(cur, tid, wid); }
;             if constexpr (Epi::PREFETCH) { if (t >= nt - 8) E.prefetch(cur, lds, tid, wid, (t - (nt - 8)) >> 1); }
;             const char* a1 = cA + (size_t)(t + 1) * kstep;
;             const char* a2 = last ? nA : cA + (size_t)(t + 2) * kstep; const char* b2 = last ? nB : cB + (size_t)(t + 2) * kstep;
;             const char* a3 = a2 + kstep; const char* b3 = b2 + kstep;
;             if (last && has_next) S.a_ready(nxt);
;             if constexpr (SP2) {
;             PG8_LDB(B0, 0, 0); PG8_LDB(B1, 0, 1); PG8_SCHED; PG8_LDA(At, 0, 0); PG8_STAGE(PG8_SA(1, 1), a1 + hstep, voffA);
;             PG8_WAIT_V(8); PG8_WAIT_L(0); PG8_BAR; PG8_MMA(0, 0, At, B0); PG8_MMA(0, 1, At, B1); PG8_BAR; PG8_SCHED;
;     ...
; #pragma unroll
;         for (int a = 0; a < 2; ++a)
; #pragma unroll
;             for (int b = 0; b < 2; ++b)
; #pragma unroll
;                 for (int m = 0; m < 4; ++m)
; #pragma unroll
;                     for (int n = 0; n < 2; ++n) acc[a][b][m][n] = (f32x4){0.f, 0.f, 0.f, 0.f};
.LBB0_86:
	s_ashr_i32 s15, s14, 31
	s_lshl_b64 s[18:19], s[14:15], 19
	s_add_u32 s18, s45, s18
	s_addc_u32 s19, s48, s19
	s_and_b64 s[20:21], s[6:7], exec
	s_cselect_b32 s15, s19, s23
	s_cselect_b32 s86, s18, s22
	s_ashr_i32 s17, s16, 31
	s_lshl_b64 s[20:21], s[16:17], 19
	s_add_u32 s20, s49, s20
	s_addc_u32 s21, s74, s21
	s_and_b64 s[70:71], s[6:7], exec
	s_cselect_b32 s87, s21, s69
	s_cselect_b32 s88, s20, s68
	s_lshl_b32 s17, s50, 8
	v_add_u32_e32 v2, s17, v157
	v_ashrrev_i32_e32 v3, 31, v2
	v_lshlrev_b64 v[4:5], 6, v[2:3]
	v_or_b32_e32 v2, 16, v2
	v_ashrrev_i32_e32 v3, 31, v2
	s_add_u32 s50, s22, 0x40080
	v_lshlrev_b64 v[2:3], 6, v[2:3]
	s_addc_u32 s51, s23, 0
	v_lshl_add_u64 v[142:143], v[136:137], 0, v[2:3]
	s_add_u32 s89, s68, 0x100
	v_mov_b32_e32 v2, 0
	v_lshl_add_u64 v[144:145], v[136:137], 0, v[4:5]
	v_lshl_add_u64 v[146:147], s[50:51], 0, v[138:139]
	v_lshl_add_u64 v[148:149], s[50:51], 0, v[140:141]
	s_addc_u32 s90, s69, 0
	s_mov_b32 s91, -2
	s_mov_b64 s[68:69], 0
	v_mov_b32_e32 v3, v2
	v_mov_b32_e32 v4, v2
	v_mov_b32_e32 v5, v2
	v_mov_b32_e32 v6, v2
	v_mov_b32_e32 v7, v2
	v_mov_b32_e32 v8, v2
	v_mov_b32_e32 v9, v2
	v_mov_b32_e32 v18, v2
	v_mov_b32_e32 v19, v2
	v_mov_b32_e32 v20, v2
	v_mov_b32_e32 v21, v2
	v_mov_b32_e32 v22, v2
	v_mov_b32_e32 v23, v2
	v_mov_b32_e32 v24, v2
	v_mov_b32_e32 v25, v2
	v_mov_b32_e32 v34, v2
	v_mov_b32_e32 v35, v2
	v_mov_b32_e32 v36, v2
	v_mov_b32_e32 v37, v2
	v_mov_b32_e32 v38, v2
	v_mov_b32_e32 v39, v2
	v_mov_b32_e32 v40, v2
	v_mov_b32_e32 v41, v2
	v_mov_b32_e32 v50, v2
	v_mov_b32_e32 v51, v2
	v_mov_b32_e32 v52, v2
	v_mov_b32_e32 v53, v2
	v_mov_b32_e32 v54, v2
	v_mov_b32_e32 v55, v2
	v_mov_b32_e32 v56, v2
	v_mov_b32_e32 v57, v2
	v_mov_b32_e32 v10, v2
	v_mov_b32_e32 v11, v2
	v_mov_b32_e32 v12, v2
	v_mov_b32_e32 v13, v2
	v_mov_b32_e32 v14, v2
	v_mov_b32_e32 v15, v2
	v_mov_b32_e32 v16, v2
	v_mov_b32_e32 v17, v2
	v_mov_b32_e32 v26, v2
	v_mov_b32_e32 v27, v2
	v_mov_b32_e32 v28, v2
	v_mov_b32_e32 v29, v2
	v_mov_b32_e32 v30, v2
	v_mov_b32_e32 v31, v2
	v_mov_b32_e32 v32, v2
	v_mov_b32_e32 v33, v2
	v_mov_b32_e32 v42, v2
	v_mov_b32_e32 v43, v2
	v_mov_b32_e32 v44, v2
	v_mov_b32_e32 v45, v2
	v_mov_b32_e32 v46, v2
	v_mov_b32_e32 v47, v2
	v_mov_b32_e32 v48, v2
	v_mov_b32_e32 v49, v2
	v_mov_b32_e32 v58, v2
	v_mov_b32_e32 v59, v2
	v_mov_b32_e32 v60, v2
	v_mov_b32_e32 v61, v2
	v_mov_b32_e32 v62, v2
	v_mov_b32_e32 v63, v2
	v_mov_b32_e32 v64, v2
	v_mov_b32_e32 v65, v2
	v_mov_b32_e32 v66, v2
	v_mov_b32_e32 v67, v2
	v_mov_b32_e32 v68, v2
	v_mov_b32_e32 v69, v2
	v_mov_b32_e32 v70, v2
	v_mov_b32_e32 v71, v2
	v_mov_b32_e32 v72, v2
	v_mov_b32_e32 v73, v2
	s_waitcnt vmcnt(0)
	v_mov_b32_e32 v82, v2
	v_mov_b32_e32 v83, v2
	v_mov_b32_e32 v84, v2
	v_mov_b32_e32 v85, v2
	v_mov_b32_e32 v86, v2
	v_mov_b32_e32 v87, v2
	v_mov_b32_e32 v88, v2
	v_mov_b32_e32 v89, v2
	v_mov_b32_e32 v98, v2
	v_mov_b32_e32 v99, v2
	v_mov_b32_e32 v100, v2
	v_mov_b32_e32 v101, v2
	v_mov_b32_e32 v102, v2
	v_mov_b32_e32 v103, v2
	v_mov_b32_e32 v104, v2
	v_mov_b32_e32 v105, v2
	v_mov_b32_e32 v114, v2
	v_mov_b32_e32 v115, v2
	v_mov_b32_e32 v116, v2
	v_mov_b32_e32 v117, v2
	v_mov_b32_e32 v118, v2
	v_mov_b32_e32 v119, v2
	v_mov_b32_e32 v120, v2
	v_mov_b32_e32 v121, v2
	v_mov_b32_e32 v74, v2
	v_mov_b32_e32 v75, v2
	v_mov_b32_e32 v76, v2
	v_mov_b32_e32 v77, v2
	v_mov_b32_e32 v78, v2
	v_mov_b32_e32 v79, v2
	v_mov_b32_e32 v80, v2
	v_mov_b32_e32 v81, v2
	v_mov_b32_e32 v90, v2
	v_mov_b32_e32 v91, v2
	v_mov_b32_e32 v92, v2
	v_mov_b32_e32 v93, v2
	v_mov_b32_e32 v94, v2
	v_mov_b32_e32 v95, v2
	v_mov_b32_e32 v96, v2
	v_mov_b32_e32 v97, v2
	v_mov_b32_e32 v106, v2
	v_mov_b32_e32 v107, v2
	v_mov_b32_e32 v108, v2
	v_mov_b32_e32 v109, v2
	v_mov_b32_e32 v110, v2
	v_mov_b32_e32 v111, v2
	v_mov_b32_e32 v112, v2
	v_mov_b32_e32 v113, v2
	v_mov_b32_e32 v122, v2
	v_mov_b32_e32 v123, v2
	v_mov_b32_e32 v124, v2
	v_mov_b32_e32 v125, v2
	v_mov_b32_e32 v126, v2
	v_mov_b32_e32 v127, v2
	v_mov_b32_e32 v128, v2
	v_mov_b32_e32 v129, v2
	v_add_u32_e32 v150, 0x10000, v153
	s_branch .LBB0_88
.LBB0_87:
	s_add_u32 s38, s22, s68
	s_addc_u32 s39, s23, s69
	s_add_u32 s38, s38, 0x100
	s_addc_u32 s39, s39, 0
	s_add_u32 s94, s38, 0x3ff80
	s_addc_u32 s95, s39, 0
	s_add_u32 s50, s89, s68
	s_addc_u32 s51, s90, s69
	s_add_i32 s92, 0, 0x10000
	s_cmpk_eq_i32 s68, 0x700
	s_cselect_b32 s73, s15, s39
	s_cselect_b32 s72, s86, s38
	s_cselect_b32 s71, s87, s51
	s_cselect_b32 s70, s88, s50
	s_add_i32 s38, 0, 0x14000
	ds_read_b128 v[170:173], v150
	ds_read_b128 v[174:177], v150 offset:1024
	ds_read_b128 v[178:181], v150 offset:2048
	ds_read_b128 v[182:185], v150 offset:3072
	ds_read_b128 v[186:189], v150 offset:16384
	ds_read_b128 v[190:193], v150 offset:17408
	ds_read_b128 v[206:209], v150 offset:18432
	ds_read_b128 v[210:213], v150 offset:19456
	s_add_i32 m0, s76, 0xc000
	ds_read_b128 v[214:217], v167
	ds_read_b128 v[218:221], v167 offset:1024
	ds_read_b128 v[222:225], v167 offset:2048
	ds_read_b128 v[226:229], v167 offset:3072
	ds_read_b128 v[230:233], v167 offset:4096
	ds_read_b128 v[234:237], v167 offset:5120
	ds_read_b128 v[238:241], v167 offset:6144
	ds_read_b128 v[242:245], v167 offset:7168
	global_load_lds_dwordx4 v138, s[94:95]
	s_add_i32 m0, s76, 0xe000
	s_nop 0
	global_load_lds_dwordx4 v140, s[94:95]
	s_waitcnt vmcnt(8)
	s_waitcnt lgkmcnt(0)
	s_setprio 1
	s_barrier
; #define PG8_STAGE(bufoff, gbase, voff) do { _Pragma("unroll") for (int _i = 0; _i < 2; ++_i) \
;         __builtin_amdgcn_global_load_lds((const unsigned*)((const char*)(gbase) + (voff)[_i]), (PG8_LAS unsigned*)(lds + (bufoff) + ldsw + _i * 8192), 16, 0, 0); } while (0)
; #define PG8_LDA(dst, b, h) do { _Pragma("unroll") for (int m = 0; m < 4; ++m) _Pragma("unroll") for (int k = 0; k < 2; ++k) dst[m][k] = *(const PG8_LAS bf16x8*)(lds + PG8_SA(b, h) + aoff + m * 2048 + k * 1024); } while (0)
; #define PG8_MMA(ai, bj, At, Bt) do { __builtin_amdgcn_s_setprio(1); _Pragma("unroll") for (int m = 0; m < 4; ++m) _Pragma("unroll") for (int n = 0; n < 2; ++n) _Pragma("unroll") for (int k = 0; k < 2; ++k) \
;         acc[ai][bj][m][n] = __builtin_amdgcn_mfma_f32_16x16x32_bf16(Bt[n][k], At[m][k], acc[ai][bj][m][n], 0, 0, 0); __builtin_amdgcn_s_setprio(0); } while (0)
; #define PG8_WAIT_V(n) asm volatile("s_waitcnt vmcnt(" #n ")" ::: "memory")
; #define PG8_WAIT_L(n) asm volatile("s_waitcnt lgkmcnt(" #n ")" ::: "memory")
; #define PG8_BAR __builtin_amdgcn_s_barrier()
; #define PG8_SCHED __builtin_amdgcn_sched_barrier(0)
; template <class Epi, class Sched, bool ALIGN_EPI = false, bool SP2 = false>
; __device__ __forceinline__ void gemm_phase(PG8_LAS unsigned char* lds, const Gemm g, const Sched& S, const Epi& E, const int tid) {
;     ...
;             PG8_WAIT_V(8); PG8_WAIT_L(0); PG8_BAR; PG8_MMA(0, 0, At, B0); PG8_MMA(0, 1, At, B1); PG8_BAR; PG8_SCHED;
;             PG8_LDA(At, 0, 1); PG8_STAGE(PG8_SB(0, 0), b2, voffB); PG8_STAGE(PG8_SB(0, 1), b2 + hstep, voffB); PG8_STAGE(PG8_SA(0, 0), a2, voffA);
;             PG8_WAIT_V(8); PG8_WAIT_L(0); PG8_BAR; PG8_MMA(1, 0, At, B0); PG8_MMA(1, 1, At, B1); PG8_BAR; PG8_SCHED;
	v_mfma_f32_16x16x32_bf16 v[126:129], v[170:173], v[214:217], v[126:129]
	v_mfma_f32_16x16x32_bf16 v[122:125], v[178:181], v[214:217], v[122:125]
	v_mfma_f32_16x16x32_bf16 v[110:113], v[170:173], v[222:225], v[110:113]
	v_mfma_f32_16x16x32_bf16 v[106:109], v[178:181], v[222:225], v[106:109]
	v_mfma_f32_16x16x32_bf16 v[94:97], v[170:173], v[230:233], v[94:97]
	v_mfma_f32_16x16x32_bf16 v[90:93], v[178:181], v[230:233], v[90:93]
	v_mfma_f32_16x16x32_bf16 v[78:81], v[170:173], v[238:241], v[78:81]
	v_mfma_f32_16x16x32_bf16 v[74:77], v[178:181], v[238:241], v[74:77]
	v_mfma_f32_16x16x32_bf16 v[126:129], v[174:177], v[218:221], v[126:129]
	v_mfma_f32_16x16x32_bf16 v[122:125], v[182:185], v[218:221], v[122:125]
	v_mfma_f32_16x16x32_bf16 v[110:113], v[174:177], v[226:229], v[110:113]
	v_mfma_f32_16x16x32_bf16 v[106:109], v[182:185], v[226:229], v[106:109]
	v_mfma_f32_16x16x32_bf16 v[94:97], v[174:177], v[234:237], v[94:97]
	v_mfma_f32_16x16x32_bf16 v[90:93], v[182:185], v[234:237], v[90:93]
	v_mfma_f32_16x16x32_bf16 v[78:81], v[174:177], v[242:245], v[78:81]
	v_mfma_f32_16x16x32_bf16 v[74:77], v[182:185], v[242:245], v[74:77]
	v_mfma_f32_16x16x32_bf16 v[118:121], v[186:189], v[214:217], v[118:121]
	v_mfma_f32_16x16x32_bf16 v[114:117], v[206:209], v[214:217], v[114:117]
	v_mfma_f32_16x16x32_bf16 v[102:105], v[186:189], v[222:225], v[102:105]
	v_mfma_f32_16x16x32_bf16 v[98:101], v[206:209], v[222:225], v[98:101]
	v_mfma_f32_16x16x32_bf16 v[86:89], v[186:189], v[230:233], v[86:89]
	v_mfma_f32_16x16x32_bf16 v[82:85], v[206:209], v[230:233], v[82:85]
	v_mfma_f32_16x16x32_bf16 v[70:73], v[186:189], v[238:241], v[70:73]
	v_mfma_f32_16x16x32_bf16 v[66:69], v[206:209], v[238:241], v[66:69]
	v_mfma_f32_16x16x32_bf16 v[118:121], v[190:193], v[218:221], v[118:121]
	v_mfma_f32_16x16x32_bf16 v[114:117], v[210:213], v[218:221], v[114:117]
	v_mfma_f32_16x16x32_bf16 v[102:105], v[190:193], v[226:229], v[102:105]
	v_mfma_f32_16x16x32_bf16 v[98:101], v[210:213], v[226:229], v[98:101]
	v_mfma_f32_16x16x32_bf16 v[86:89], v[190:193], v[234:237], v[86:89]
	v_mfma_f32_16x16x32_bf16 v[82:85], v[210:213], v[234:237], v[82:85]
	v_mfma_f32_16x16x32_bf16 v[70:73], v[190:193], v[242:245], v[70:73]
	v_mfma_f32_16x16x32_bf16 v[66:69], v[210:213], v[242:245], v[66:69]
	s_setprio 0
	s_barrier
	s_add_i32 s39, s92, s75
	s_mov_b32 m0, s39
	ds_read_b128 v[214:217], v167 offset:16384
	ds_read_b128 v[218:221], v167 offset:17408
	ds_read_b128 v[222:225], v167 offset:18432
	ds_read_b128 v[226:229], v167 offset:19456
	ds_read_b128 v[230:233], v167 offset:20480
	ds_read_b128 v[234:237], v167 offset:21504
	ds_read_b128 v[238:241], v167 offset:22528
	ds_read_b128 v[242:245], v167 offset:23552
	global_load_lds_dwordx4 v0, s[70:71]
	s_add_i32 m0, s39, 0x2000
	s_add_u32 s50, s70, 0x40000
	s_addc_u32 s51, s71, 0
	s_add_i32 s38, s38, s75
	global_load_lds_dwordx4 v130, s[70:71]
	s_mov_b32 m0, s38
	s_nop 0
	global_load_lds_dwordx4 v0, s[50:51]
	s_add_i32 m0, s38, 0x2000
	s_nop 0
	global_load_lds_dwordx4 v130, s[50:51]
	s_mov_b32 m0, s76
	s_nop 0
	global_load_lds_dwordx4 v134, s[72:73]
	s_mov_b32 m0, s77
	s_nop 0
	global_load_lds_dwordx4 v132, s[72:73]
	s_waitcnt vmcnt(8)
	s_waitcnt lgkmcnt(0)
	s_setprio 1
	s_barrier
	v_mfma_f32_16x16x32_bf16 v[62:65], v[170:173], v[214:217], v[62:65]
	v_mfma_f32_16x16x32_bf16 v[58:61], v[178:181], v[214:217], v[58:61]
	v_mfma_f32_16x16x32_bf16 v[46:49], v[170:173], v[222:225], v[46:49]
	v_mfma_f32_16x16x32_bf16 v[42:45], v[178:181], v[222:225], v[42:45]
	v_mfma_f32_16x16x32_bf16 v[30:33], v[170:173], v[230:233], v[30:33]
	v_mfma_f32_16x16x32_bf16 v[26:29], v[178:181], v[230:233], v[26:29]
	v_mfma_f32_16x16x32_bf16 v[14:17], v[170:173], v[238:241], v[14:17]
	v_mfma_f32_16x16x32_bf16 v[10:13], v[178:181], v[238:241], v[10:13]
	v_mfma_f32_16x16x32_bf16 v[62:65], v[174:177], v[218:221], v[62:65]
	v_mfma_f32_16x16x32_bf16 v[58:61], v[182:185], v[218:221], v[58:61]
	v_mfma_f32_16x16x32_bf16 v[46:49], v[174:177], v[226:229], v[46:49]
	v_mfma_f32_16x16x32_bf16 v[42:45], v[182:185], v[226:229], v[42:45]
	v_mfma_f32_16x16x32_bf16 v[30:33], v[174:177], v[234:237], v[30:33]
	v_mfma_f32_16x16x32_bf16 v[26:29], v[182:185], v[234:237], v[26:29]
	v_mfma_f32_16x16x32_bf16 v[14:17], v[174:177], v[242:245], v[14:17]
	v_mfma_f32_16x16x32_bf16 v[10:13], v[182:185], v[242:245], v[10:13]
	v_mfma_f32_16x16x32_bf16 v[54:57], v[186:189], v[214:217], v[54:57]
	v_mfma_f32_16x16x32_bf16 v[50:53], v[206:209], v[214:217], v[50:53]
	v_mfma_f32_16x16x32_bf16 v[38:41], v[186:189], v[222:225], v[38:41]
	v_mfma_f32_16x16x32_bf16 v[34:37], v[206:209], v[222:225], v[34:37]
	v_mfma_f32_16x16x32_bf16 v[22:25], v[186:189], v[230:233], v[22:25]
	v_mfma_f32_16x16x32_bf16 v[18:21], v[206:209], v[230:233], v[18:21]
	v_mfma_f32_16x16x32_bf16 v[6:9], v[186:189], v[238:241], v[6:9]
	v_mfma_f32_16x16x32_bf16 v[2:5], v[206:209], v[238:241], v[2:5]
	v_mfma_f32_16x16x32_bf16 v[54:57], v[190:193], v[218:221], v[54:57]
	v_mfma_f32_16x16x32_bf16 v[50:53], v[210:213], v[218:221], v[50:53]
	v_mfma_f32_16x16x32_bf16 v[38:41], v[190:193], v[226:229], v[38:41]
	v_mfma_f32_16x16x32_bf16 v[34:37], v[210:213], v[226:229], v[34:37]
	v_mfma_f32_16x16x32_bf16 v[22:25], v[190:193], v[234:237], v[22:25]
	v_mfma_f32_16x16x32_bf16 v[18:21], v[210:213], v[234:237], v[18:21]
	v_mfma_f32_16x16x32_bf16 v[6:9], v[190:193], v[242:245], v[6:9]
	v_mfma_f32_16x16x32_bf16 v[2:5], v[210:213], v[242:245], v[2:5]
	s_setprio 0
	s_barrier
; #define PG8_STAGE(bufoff, gbase, voff) do { _Pragma("unroll") for (int _i = 0; _i < 2; ++_i) \
;         __builtin_amdgcn_global_load_lds((const unsigned*)((const char*)(gbase) + (voff)[_i]), (PG8_LAS unsigned*)(lds + (bufoff) + ldsw + _i * 8192), 16, 0, 0); } while (0)
; #define PG8_LDA(dst, b, h) do { _Pragma("unroll") for (int m = 0; m < 4; ++m) _Pragma("unroll") for (int k = 0; k < 2; ++k) dst[m][k] = *(const PG8_LAS bf16x8*)(lds + PG8_SA(b, h) + aoff + m * 2048 + k * 1024); } while (0)
; #define PG8_LDB(dst, b, h) do { _Pragma("unroll") for (int n = 0; n < 2; ++n) _Pragma("unroll") for (int k = 0; k < 2; ++k) dst[n][k] = *(const PG8_LAS bf16x8*)(lds + PG8_SB(b, h) + boff + n * 2048 + k * 1024); } while (0)
; #define PG8_MMA(ai, bj, At, Bt) do { __builtin_amdgcn_s_setprio(1); _Pragma("unroll") for (int m = 0; m < 4; ++m) _Pragma("unroll") for (int n = 0; n < 2; ++n) _Pragma("unroll") for (int k = 0; k < 2; ++k) \
;         acc[ai][bj][m][n] = __builtin_amdgcn_mfma_f32_16x16x32_bf16(Bt[n][k], At[m][k], acc[ai][bj][m][n], 0, 0, 0); __builtin_amdgcn_s_setprio(0); } while (0)
; #define PG8_WAIT_V(n) asm volatile("s_waitcnt vmcnt(" #n ")" ::: "memory")
; #define PG8_WAIT_L(n) asm volatile("s_waitcnt lgkmcnt(" #n ")" ::: "memory")
; #define PG8_BAR __builtin_amdgcn_s_barrier()
; #define PG8_SCHED __builtin_amdgcn_sched_barrier(0)
; template <class Epi, class Sched, bool ALIGN_EPI = false, bool SP2 = false>
; __device__ __forceinline__ void gemm_phase(PG8_LAS unsigned char* lds, const Gemm g, const Sched& S, const Epi& E, const int tid) {
;     ...
;             PG8_LDB(B0, 1, 0); PG8_LDB(B1, 1, 1); PG8_SCHED; PG8_LDA(At, 1, 0); PG8_STAGE(PG8_SA(0, 1), a2 + hstep, voffA);
;             PG8_WAIT_V(8); PG8_WAIT_L(0); PG8_BAR; PG8_MMA(0, 0, At, B0); PG8_MMA(0, 1, At, B1); PG8_BAR; PG8_SCHED;
;             PG8_LDA(At, 1, 1); PG8_STAGE(PG8_SB(1, 0), b3, voffB); PG8_STAGE(PG8_SB(1, 1), b3 + hstep, voffB); PG8_STAGE(PG8_SA(1, 0), a3, voffA);
;             PG8_WAIT_V(8); PG8_WAIT_L(0); PG8_BAR; PG8_MMA(1, 0, At, B0); PG8_MMA(1, 1, At, B1); PG8_BAR; PG8_SCHED;
	s_add_i32 s38, 0, 0x18000
	s_add_i32 s39, 0, 0x1c000
	ds_read_b128 v[170:173], v150 offset:32768
	ds_read_b128 v[174:177], v150 offset:33792
	ds_read_b128 v[178:181], v150 offset:34816
	ds_read_b128 v[182:185], v150 offset:35840
	ds_read_b128 v[186:189], v150 offset:49152
	ds_read_b128 v[190:193], v150 offset:50176
	ds_read_b128 v[206:209], v150 offset:51200
	ds_read_b128 v[210:213], v150 offset:52224
	s_add_u32 s50, s72, 0x40000
	s_addc_u32 s51, s73, 0
	s_mov_b32 m0, s78
	ds_read_b128 v[214:217], v167 offset:32768
	ds_read_b128 v[218:221], v167 offset:33792
	ds_read_b128 v[222:225], v167 offset:34816
	ds_read_b128 v[226:229], v167 offset:35840
	ds_read_b128 v[230:233], v167 offset:36864
	ds_read_b128 v[234:237], v167 offset:37888
	ds_read_b128 v[238:241], v167 offset:38912
	ds_read_b128 v[242:245], v167 offset:39936
	global_load_lds_dwordx4 v134, s[50:51]
	s_mov_b32 m0, s79
	s_nop 0
	global_load_lds_dwordx4 v132, s[50:51]
	s_waitcnt vmcnt(8)
	s_waitcnt lgkmcnt(0)
	s_setprio 1
	s_barrier
	v_mfma_f32_16x16x32_bf16 v[126:129], v[170:173], v[214:217], v[126:129]
	v_mfma_f32_16x16x32_bf16 v[122:125], v[178:181], v[214:217], v[122:125]
	v_mfma_f32_16x16x32_bf16 v[110:113], v[170:173], v[222:225], v[110:113]
	v_mfma_f32_16x16x32_bf16 v[106:109], v[178:181], v[222:225], v[106:109]
	v_mfma_f32_16x16x32_bf16 v[94:97], v[170:173], v[230:233], v[94:97]
	v_mfma_f32_16x16x32_bf16 v[90:93], v[178:181], v[230:233], v[90:93]
	v_mfma_f32_16x16x32_bf16 v[78:81], v[170:173], v[238:241], v[78:81]
	v_mfma_f32_16x16x32_bf16 v[74:77], v[178:181], v[238:241], v[74:77]
	v_mfma_f32_16x16x32_bf16 v[126:129], v[174:177], v[218:221], v[126:129]
	v_mfma_f32_16x16x32_bf16 v[122:125], v[182:185], v[218:221], v[122:125]
	v_mfma_f32_16x16x32_bf16 v[110:113], v[174:177], v[226:229], v[110:113]
	v_mfma_f32_16x16x32_bf16 v[106:109], v[182:185], v[226:229], v[106:109]
	v_mfma_f32_16x16x32_bf16 v[94:97], v[174:177], v[234:237], v[94:97]
	v_mfma_f32_16x16x32_bf16 v[90:93], v[182:185], v[234:237], v[90:93]
	v_mfma_f32_16x16x32_bf16 v[78:81], v[174:177], v[242:245], v[78:81]
	v_mfma_f32_16x16x32_bf16 v[74:77], v[182:185], v[242:245], v[74:77]
	v_mfma_f32_16x16x32_bf16 v[118:121], v[186:189], v[214:217], v[118:121]
	v_mfma_f32_16x16x32_bf16 v[114:117], v[206:209], v[214:217], v[114:117]
	v_mfma_f32_16x16x32_bf16 v[102:105], v[186:189], v[222:225], v[102:105]
	v_mfma_f32_16x16x32_bf16 v[98:101], v[206:209], v[222:225], v[98:101]
	v_mfma_f32_16x16x32_bf16 v[86:89], v[186:189], v[230:233], v[86:89]
	v_mfma_f32_16x16x32_bf16 v[82:85], v[206:209], v[230:233], v[82:85]
	v_mfma_f32_16x16x32_bf16 v[70:73], v[186:189], v[238:241], v[70:73]
	v_mfma_f32_16x16x32_bf16 v[66:69], v[206:209], v[238:241], v[66:69]
	v_mfma_f32_16x16x32_bf16 v[118:121], v[190:193], v[218:221], v[118:121]
	v_mfma_f32_16x16x32_bf16 v[114:117], v[210:213], v[218:221], v[114:117]
	v_mfma_f32_16x16x32_bf16 v[102:105], v[190:193], v[226:229], v[102:105]
	v_mfma_f32_16x16x32_bf16 v[98:101], v[210:213], v[226:229], v[98:101]
	v_mfma_f32_16x16x32_bf16 v[86:89], v[190:193], v[234:237], v[86:89]
	v_mfma_f32_16x16x32_bf16 v[82:85], v[210:213], v[234:237], v[82:85]
	v_mfma_f32_16x16x32_bf16 v[70:73], v[190:193], v[242:245], v[70:73]
	v_mfma_f32_16x16x32_bf16 v[66:69], v[210:213], v[242:245], v[66:69]
	s_setprio 0
	s_barrier
	s_add_i32 s38, s38, s75
	s_add_u32 s94, s70, 0x80
	s_addc_u32 s95, s71, 0
	s_mov_b32 m0, s38
	ds_read_b128 v[214:217], v167 offset:49152
	ds_read_b128 v[218:221], v167 offset:50176
	ds_read_b128 v[222:225], v167 offset:51200
	ds_read_b128 v[226:229], v167 offset:52224
	ds_read_b128 v[230:233], v167 offset:53248
	ds_read_b128 v[234:237], v167 offset:54272
	ds_read_b128 v[238:241], v167 offset:55296
	ds_read_b128 v[242:245], v167 offset:56320
	global_load_lds_dwordx4 v0, s[94:95]
	s_add_i32 m0, s38, 0x2000
	s_add_u32 s50, s70, 0x40080
	s_addc_u32 s51, s71, 0
	s_add_i32 s38, s39, s75
	global_load_lds_dwordx4 v130, s[94:95]
	s_mov_b32 m0, s38
	s_nop 0
	global_load_lds_dwordx4 v0, s[50:51]
	s_add_i32 m0, s38, 0x2000
	s_nop 0
	global_load_lds_dwordx4 v130, s[50:51]
	s_add_u32 s94, s72, 0x80
	s_addc_u32 s95, s73, 0
	s_mov_b32 m0, s80
	s_nop 0
	global_load_lds_dwordx4 v134, s[94:95]
	s_mov_b32 m0, s81
	s_nop 0
	global_load_lds_dwordx4 v132, s[94:95]
	s_waitcnt vmcnt(8)
	s_waitcnt lgkmcnt(0)
	s_setprio 1
	s_barrier
	v_mfma_f32_16x16x32_bf16 v[62:65], v[170:173], v[214:217], v[62:65]
	v_mfma_f32_16x16x32_bf16 v[58:61], v[178:181], v[214:217], v[58:61]
	v_mfma_f32_16x16x32_bf16 v[46:49], v[170:173], v[222:225], v[46:49]
	v_mfma_f32_16x16x32_bf16 v[42:45], v[178:181], v[222:225], v[42:45]
	v_mfma_f32_16x16x32_bf16 v[30:33], v[170:173], v[230:233], v[30:33]
	v_mfma_f32_16x16x32_bf16 v[26:29], v[178:181], v[230:233], v[26:29]
	v_mfma_f32_16x16x32_bf16 v[14:17], v[170:173], v[238:241], v[14:17]
	v_mfma_f32_16x16x32_bf16 v[10:13], v[178:181], v[238:241], v[10:13]
	v_mfma_f32_16x16x32_bf16 v[62:65], v[174:177], v[218:221], v[62:65]
	v_mfma_f32_16x16x32_bf16 v[58:61], v[182:185], v[218:221], v[58:61]
	v_mfma_f32_16x16x32_bf16 v[46:49], v[174:177], v[226:229], v[46:49]
	v_mfma_f32_16x16x32_bf16 v[42:45], v[182:185], v[226:229], v[42:45]
	v_mfma_f32_16x16x32_bf16 v[30:33], v[174:177], v[234:237], v[30:33]
	v_mfma_f32_16x16x32_bf16 v[26:29], v[182:185], v[234:237], v[26:29]
	v_mfma_f32_16x16x32_bf16 v[14:17], v[174:177], v[242:245], v[14:17]
	v_mfma_f32_16x16x32_bf16 v[10:13], v[182:185], v[242:245], v[10:13]
	v_mfma_f32_16x16x32_bf16 v[54:57], v[186:189], v[214:217], v[54:57]
	v_mfma_f32_16x16x32_bf16 v[50:53], v[206:209], v[214:217], v[50:53]
	v_mfma_f32_16x16x32_bf16 v[38:41], v[186:189], v[222:225], v[38:41]
	v_mfma_f32_16x16x32_bf16 v[34:37], v[206:209], v[222:225], v[34:37]
	v_mfma_f32_16x16x32_bf16 v[22:25], v[186:189], v[230:233], v[22:25]
	v_mfma_f32_16x16x32_bf16 v[18:21], v[206:209], v[230:233], v[18:21]
	v_mfma_f32_16x16x32_bf16 v[6:9], v[186:189], v[238:241], v[6:9]
	v_mfma_f32_16x16x32_bf16 v[2:5], v[206:209], v[238:241], v[2:5]
	v_mfma_f32_16x16x32_bf16 v[54:57], v[190:193], v[218:221], v[54:57]
	v_mfma_f32_16x16x32_bf16 v[50:53], v[210:213], v[218:221], v[50:53]
	v_mfma_f32_16x16x32_bf16 v[38:41], v[190:193], v[226:229], v[38:41]
	v_mfma_f32_16x16x32_bf16 v[34:37], v[210:213], v[226:229], v[34:37]
	v_mfma_f32_16x16x32_bf16 v[22:25], v[190:193], v[234:237], v[22:25]
	v_mfma_f32_16x16x32_bf16 v[18:21], v[210:213], v[234:237], v[18:21]
	v_mfma_f32_16x16x32_bf16 v[6:9], v[190:193], v[242:245], v[6:9]
	v_mfma_f32_16x16x32_bf16 v[2:5], v[210:213], v[242:245], v[2:5]
	s_setprio 0
	s_barrier
	s_add_i32 s91, s91, 2
	s_add_u32 s68, s68, 0x100
	s_addc_u32 s69, s69, 0
	s_cmp_gt_u32 s91, 13
	s_cbranch_scc1 .LBB0_90

;     __device__ __forceinline__ void stage_rs(const Unit& u, int tid, int wid) const { stage_rs_lds(SS, rsl, u, tid, wid); }
;     __device__ __forceinline__ void stage_rs(const Unit& u, int tid, int wid) const { stage_rs_lds(SS, rsl, u, tid, wid); }
; #define PG8_STAGE(bufoff, gbase, voff) do { _Pragma("unroll") for (int _i = 0; _i < 2; ++_i) \
;         __builtin_amdgcn_global_load_lds((const unsigned*)((const char*)(gbase) + (voff)[_i]), (PG8_LAS unsigned*)(lds + (bufoff) + ldsw + _i * 8192), 16, 0, 0); } while (0)
; #define PG8_LDA(dst, b, h) do { _Pragma("unroll") for (int m = 0; m < 4; ++m) _Pragma("unroll") for (int k = 0; k < 2; ++k) dst[m][k] = *(const PG8_LAS bf16x8*)(lds + PG8_SA(b, h) + aoff + m * 2048 + k * 1024); } while (0)
; #define PG8_LDB(dst, b, h) do { _Pragma("unroll") for (int n = 0; n < 2; ++n) _Pragma("unroll") for (int k = 0; k < 2; ++k) dst[n][k] = *(const PG8_LAS bf16x8*)(lds + PG8_SB(b, h) + boff + n * 2048 + k * 1024); } while (0)
; #define PG8_BAR __builtin_amdgcn_s_barrier()
; template <class Epi, class Sched, bool ALIGN_EPI = false, bool SP2 = false>
; __device__ __forceinline__ void gemm_phase(PG8_LAS unsigned char* lds, const Gemm g, const Sched& S, const Epi& E, const int tid) {
;     ...
;             const bool last = (t == nt - 2);
;             if constexpr (Epi::RS_LDS) { if (t == nt - 4) E.stage_rs(cur, tid, wid); }
;             if constexpr (Epi::PREFETCH) { if (t >= nt - 8) E.prefetch(cur, lds, tid, wid, (t - (nt - 8)) >> 1); }
;             const char* a1 = cA + (size_t)(t + 1) * kstep;
;             const char* a2 = last ? nA : cA + (size_t)(t + 2) * kstep; const char* b2 = last ? nB : cB + (size_t)(t + 2) * kstep;
;             const char* a3 = a2 + kstep; const char* b3 = b2 + kstep;
;             if (last && has_next) S.a_ready(nxt);
;             if constexpr (SP2) {
;             PG8_LDB(B0, 0, 0); PG8_LDB(B1, 0, 1); PG8_SCHED; PG8_LDA(At, 0, 0); PG8_STAGE(PG8_SA(1, 1), a1 + hstep, voffA);
;             PG8_WAIT_V(8); PG8_WAIT_L(0); PG8_BAR; PG8_MMA(0, 0, At, B0); PG8_MMA(0, 1, At, B1); PG8_BAR; PG8_SCHED;
;     ...
; #pragma unroll
;         for (int a = 0; a < 2; ++a)
; #pragma unroll
;             for (int b = 0; b < 2; ++b)
; #pragma unroll
;                 for (int m = 0; m < 4; ++m)
; #pragma unroll
;                     for (int n = 0; n < 2; ++n) acc[a][b][m][n] = (f32x4){0.f, 0.f, 0.f, 0.f};
.LBB0_207:
	s_ashr_i32 s23, s22, 31
	s_lshl_b64 s[50:51], s[22:23], 19
	s_add_u32 s70, s45, s50
	s_addc_u32 s71, s80, s51
	s_and_b64 s[50:51], s[8:9], exec
	s_cselect_b32 s49, s71, s11
	s_cselect_b32 s78, s70, s10
	s_ashr_i32 s69, s68, 31
	s_lshl_b64 s[50:51], s[68:69], 19
	s_add_u32 s72, s81, s50
	s_addc_u32 s73, s82, s51
	s_and_b64 s[50:51], s[8:9], exec
	s_cselect_b32 s69, s73, s13
	s_cselect_b32 s79, s72, s12
	s_lshl_b32 s23, s48, 8
	s_waitcnt lgkmcnt(0)
	v_add_u32_e32 v2, s23, v157
	v_ashrrev_i32_e32 v3, 31, v2
	v_lshlrev_b64 v[4:5], 6, v[2:3]
	v_or_b32_e32 v2, 16, v2
	v_ashrrev_i32_e32 v3, 31, v2
	s_add_u32 s50, s10, 0x40080
	v_lshlrev_b64 v[2:3], 6, v[2:3]
	s_addc_u32 s51, s11, 0
	v_lshl_add_u64 v[144:145], v[138:139], 0, v[2:3]
	s_add_u32 vcc_lo, s12, 0x100
	v_mov_b32_e32 v2, 0
	v_lshl_add_u64 v[146:147], v[138:139], 0, v[4:5]
	v_add_u32_e32 v148, 0x3ff80, v140
	v_add_u32_e32 v150, 0x3ff80, v142
	s_addc_u32 vcc_hi, s13, 0
	s_mov_b32 s50, -2
	s_mov_b64 s[12:13], 0
	v_mov_b32_e32 v3, v2
	v_mov_b32_e32 v4, v2
	v_mov_b32_e32 v5, v2
	v_mov_b32_e32 v6, v2
	v_mov_b32_e32 v7, v2
	v_mov_b32_e32 v8, v2
	v_mov_b32_e32 v9, v2
	v_mov_b32_e32 v18, v2
	v_mov_b32_e32 v19, v2
	v_mov_b32_e32 v20, v2
	v_mov_b32_e32 v21, v2
	v_mov_b32_e32 v22, v2
	v_mov_b32_e32 v23, v2
	v_mov_b32_e32 v24, v2
	v_mov_b32_e32 v25, v2
	v_mov_b32_e32 v34, v2
	v_mov_b32_e32 v35, v2
	v_mov_b32_e32 v36, v2
	v_mov_b32_e32 v37, v2
	v_mov_b32_e32 v38, v2
	v_mov_b32_e32 v39, v2
	v_mov_b32_e32 v40, v2
	v_mov_b32_e32 v41, v2
	v_mov_b32_e32 v50, v2
	v_mov_b32_e32 v51, v2
	v_mov_b32_e32 v52, v2
	v_mov_b32_e32 v53, v2
	v_mov_b32_e32 v54, v2
	v_mov_b32_e32 v55, v2
	v_mov_b32_e32 v56, v2
	v_mov_b32_e32 v57, v2
	v_mov_b32_e32 v10, v2
	v_mov_b32_e32 v11, v2
	v_mov_b32_e32 v12, v2
	v_mov_b32_e32 v13, v2
	v_mov_b32_e32 v14, v2
	v_mov_b32_e32 v15, v2
	v_mov_b32_e32 v16, v2
	v_mov_b32_e32 v17, v2
	v_mov_b32_e32 v26, v2
	v_mov_b32_e32 v27, v2
	v_mov_b32_e32 v28, v2
	v_mov_b32_e32 v29, v2
	v_mov_b32_e32 v30, v2
	v_mov_b32_e32 v31, v2
	v_mov_b32_e32 v32, v2
	v_mov_b32_e32 v33, v2
	v_mov_b32_e32 v42, v2
	v_mov_b32_e32 v43, v2
	v_mov_b32_e32 v44, v2
	v_mov_b32_e32 v45, v2
	v_mov_b32_e32 v46, v2
	v_mov_b32_e32 v47, v2
	v_mov_b32_e32 v48, v2
	v_mov_b32_e32 v49, v2
	v_mov_b32_e32 v58, v2
	v_mov_b32_e32 v59, v2
	v_mov_b32_e32 v60, v2
	v_mov_b32_e32 v61, v2
	v_mov_b32_e32 v62, v2
	v_mov_b32_e32 v63, v2
	v_mov_b32_e32 v64, v2
	v_mov_b32_e32 v65, v2
	v_mov_b32_e32 v66, v2
	v_mov_b32_e32 v67, v2
	v_mov_b32_e32 v68, v2
	v_mov_b32_e32 v69, v2
	v_mov_b32_e32 v70, v2
	v_mov_b32_e32 v71, v2
	v_mov_b32_e32 v72, v2
	v_mov_b32_e32 v73, v2
	s_waitcnt vmcnt(0)
	v_mov_b32_e32 v82, v2
	v_mov_b32_e32 v83, v2
	v_mov_b32_e32 v84, v2
	v_mov_b32_e32 v85, v2
	v_mov_b32_e32 v86, v2
	v_mov_b32_e32 v87, v2
	v_mov_b32_e32 v88, v2
	v_mov_b32_e32 v89, v2
	v_mov_b32_e32 v98, v2
	v_mov_b32_e32 v99, v2
	v_mov_b32_e32 v100, v2
	v_mov_b32_e32 v101, v2
	v_mov_b32_e32 v102, v2
	v_mov_b32_e32 v103, v2
	v_mov_b32_e32 v104, v2
	v_mov_b32_e32 v105, v2
	v_mov_b32_e32 v114, v2
	v_mov_b32_e32 v115, v2
	v_mov_b32_e32 v116, v2
	v_mov_b32_e32 v117, v2
	v_mov_b32_e32 v118, v2
	v_mov_b32_e32 v119, v2
	v_mov_b32_e32 v120, v2
	v_mov_b32_e32 v121, v2
	v_mov_b32_e32 v74, v2
	v_mov_b32_e32 v75, v2
	v_mov_b32_e32 v76, v2
	v_mov_b32_e32 v77, v2
	v_mov_b32_e32 v78, v2
	v_mov_b32_e32 v79, v2
	v_mov_b32_e32 v80, v2
	v_mov_b32_e32 v81, v2
	v_mov_b32_e32 v90, v2
	v_mov_b32_e32 v91, v2
	v_mov_b32_e32 v92, v2
	v_mov_b32_e32 v93, v2
	v_mov_b32_e32 v94, v2
	v_mov_b32_e32 v95, v2
	v_mov_b32_e32 v96, v2
	v_mov_b32_e32 v97, v2
	v_mov_b32_e32 v106, v2
	v_mov_b32_e32 v107, v2
	v_mov_b32_e32 v108, v2
	v_mov_b32_e32 v109, v2
	v_mov_b32_e32 v110, v2
	v_mov_b32_e32 v111, v2
	v_mov_b32_e32 v112, v2
	v_mov_b32_e32 v113, v2
	v_mov_b32_e32 v122, v2
	v_mov_b32_e32 v123, v2
	v_mov_b32_e32 v124, v2
	v_mov_b32_e32 v125, v2
	v_mov_b32_e32 v126, v2
	v_mov_b32_e32 v127, v2
	v_mov_b32_e32 v128, v2
	v_mov_b32_e32 v129, v2
	v_add_u32_e32 v0, 0x10000, v153
	s_branch .LBB0_209
.LBB0_208:
	s_add_u32 s38, s10, s12
	s_addc_u32 s39, s11, s13
	s_add_u32 s38, s38, 0x100
	s_addc_u32 s39, s39, 0
	s_add_u32 s51, vcc_lo, s12
	s_addc_u32 s74, vcc_hi, s13
	s_add_i32 s59, 0, 0x10000
	s_cmpk_eq_i32 s12, 0x700
	s_cselect_b32 s77, s49, s39
	s_cselect_b32 s76, s78, s38
	s_cselect_b32 s75, s69, s74
	s_cselect_b32 s74, s79, s51
	s_add_i32 s51, 0, 0x14000
	ds_read_b128 v[170:173], v0
	ds_read_b128 v[174:177], v0 offset:1024
	ds_read_b128 v[178:181], v0 offset:2048
	ds_read_b128 v[182:185], v0 offset:3072
	ds_read_b128 v[186:189], v0 offset:16384
	ds_read_b128 v[190:193], v0 offset:17408
	ds_read_b128 v[206:209], v0 offset:18432
	ds_read_b128 v[210:213], v0 offset:19456
	s_add_i32 m0, s84, 0xc000
	ds_read_b128 v[214:217], v167
	ds_read_b128 v[218:221], v167 offset:1024
	ds_read_b128 v[222:225], v167 offset:2048
	ds_read_b128 v[226:229], v167 offset:3072
	ds_read_b128 v[230:233], v167 offset:4096
	ds_read_b128 v[234:237], v167 offset:5120
	ds_read_b128 v[238:241], v167 offset:6144
	ds_read_b128 v[242:245], v167 offset:7168
	global_load_lds_dwordx4 v148, s[38:39]
	s_add_i32 m0, s84, 0xe000
	s_nop 0
	global_load_lds_dwordx4 v150, s[38:39]
	s_waitcnt vmcnt(8)
	s_waitcnt lgkmcnt(0)
	s_setprio 1
	s_barrier
; #define PG8_STAGE(bufoff, gbase, voff) do { _Pragma("unroll") for (int _i = 0; _i < 2; ++_i) \
;         __builtin_amdgcn_global_load_lds((const unsigned*)((const char*)(gbase) + (voff)[_i]), (PG8_LAS unsigned*)(lds + (bufoff) + ldsw + _i * 8192), 16, 0, 0); } while (0)
; #define PG8_LDA(dst, b, h) do { _Pragma("unroll") for (int m = 0; m < 4; ++m) _Pragma("unroll") for (int k = 0; k < 2; ++k) dst[m][k] = *(const PG8_LAS bf16x8*)(lds + PG8_SA(b, h) + aoff + m * 2048 + k * 1024); } while (0)
; #define PG8_MMA(ai, bj, At, Bt) do { __builtin_amdgcn_s_setprio(1); _Pragma("unroll") for (int m = 0; m < 4; ++m) _Pragma("unroll") for (int n = 0; n < 2; ++n) _Pragma("unroll") for (int k = 0; k < 2; ++k) \
;         acc[ai][bj][m][n] = __builtin_amdgcn_mfma_f32_16x16x32_bf16(Bt[n][k], At[m][k], acc[ai][bj][m][n], 0, 0, 0); __builtin_amdgcn_s_setprio(0); } while (0)
; #define PG8_WAIT_V(n) asm volatile("s_waitcnt vmcnt(" #n ")" ::: "memory")
; #define PG8_WAIT_L(n) asm volatile("s_waitcnt lgkmcnt(" #n ")" ::: "memory")
; #define PG8_BAR __builtin_amdgcn_s_barrier()
; #define PG8_SCHED __builtin_amdgcn_sched_barrier(0)
; template <class Epi, class Sched, bool ALIGN_EPI = false, bool SP2 = false>
; __device__ __forceinline__ void gemm_phase(PG8_LAS unsigned char* lds, const Gemm g, const Sched& S, const Epi& E, const int tid) {
;     ...
;             PG8_WAIT_V(8); PG8_WAIT_L(0); PG8_BAR; PG8_MMA(0, 0, At, B0); PG8_MMA(0, 1, At, B1); PG8_BAR; PG8_SCHED;
;             PG8_LDA(At, 0, 1); PG8_STAGE(PG8_SB(0, 0), b2, voffB); PG8_STAGE(PG8_SB(0, 1), b2 + hstep, voffB); PG8_STAGE(PG8_SA(0, 0), a2, voffA);
;             PG8_WAIT_V(8); PG8_WAIT_L(0); PG8_BAR; PG8_MMA(1, 0, At, B0); PG8_MMA(1, 1, At, B1); PG8_BAR; PG8_SCHED;
	v_mfma_f32_16x16x32_bf16 v[126:129], v[170:173], v[214:217], v[126:129]
	v_mfma_f32_16x16x32_bf16 v[122:125], v[178:181], v[214:217], v[122:125]
	v_mfma_f32_16x16x32_bf16 v[110:113], v[170:173], v[222:225], v[110:113]
	v_mfma_f32_16x16x32_bf16 v[106:109], v[178:181], v[222:225], v[106:109]
	v_mfma_f32_16x16x32_bf16 v[94:97], v[170:173], v[230:233], v[94:97]
	v_mfma_f32_16x16x32_bf16 v[90:93], v[178:181], v[230:233], v[90:93]
	v_mfma_f32_16x16x32_bf16 v[78:81], v[170:173], v[238:241], v[78:81]
	v_mfma_f32_16x16x32_bf16 v[74:77], v[178:181], v[238:241], v[74:77]
	v_mfma_f32_16x16x32_bf16 v[126:129], v[174:177], v[218:221], v[126:129]
	v_mfma_f32_16x16x32_bf16 v[122:125], v[182:185], v[218:221], v[122:125]
	v_mfma_f32_16x16x32_bf16 v[110:113], v[174:177], v[226:229], v[110:113]
	v_mfma_f32_16x16x32_bf16 v[106:109], v[182:185], v[226:229], v[106:109]
	v_mfma_f32_16x16x32_bf16 v[94:97], v[174:177], v[234:237], v[94:97]
	v_mfma_f32_16x16x32_bf16 v[90:93], v[182:185], v[234:237], v[90:93]
	v_mfma_f32_16x16x32_bf16 v[78:81], v[174:177], v[242:245], v[78:81]
	v_mfma_f32_16x16x32_bf16 v[74:77], v[182:185], v[242:245], v[74:77]
	v_mfma_f32_16x16x32_bf16 v[118:121], v[186:189], v[214:217], v[118:121]
	v_mfma_f32_16x16x32_bf16 v[114:117], v[206:209], v[214:217], v[114:117]
	v_mfma_f32_16x16x32_bf16 v[102:105], v[186:189], v[222:225], v[102:105]
	v_mfma_f32_16x16x32_bf16 v[98:101], v[206:209], v[222:225], v[98:101]
	v_mfma_f32_16x16x32_bf16 v[86:89], v[186:189], v[230:233], v[86:89]
	v_mfma_f32_16x16x32_bf16 v[82:85], v[206:209], v[230:233], v[82:85]
	v_mfma_f32_16x16x32_bf16 v[70:73], v[186:189], v[238:241], v[70:73]
	v_mfma_f32_16x16x32_bf16 v[66:69], v[206:209], v[238:241], v[66:69]
	v_mfma_f32_16x16x32_bf16 v[118:121], v[190:193], v[218:221], v[118:121]
	v_mfma_f32_16x16x32_bf16 v[114:117], v[210:213], v[218:221], v[114:117]
	v_mfma_f32_16x16x32_bf16 v[102:105], v[190:193], v[226:229], v[102:105]
	v_mfma_f32_16x16x32_bf16 v[98:101], v[210:213], v[226:229], v[98:101]
	v_mfma_f32_16x16x32_bf16 v[86:89], v[190:193], v[234:237], v[86:89]
	v_mfma_f32_16x16x32_bf16 v[82:85], v[210:213], v[234:237], v[82:85]
	v_mfma_f32_16x16x32_bf16 v[70:73], v[190:193], v[242:245], v[70:73]
	v_mfma_f32_16x16x32_bf16 v[66:69], v[210:213], v[242:245], v[66:69]
	s_setprio 0
	s_barrier
	s_add_i32 s38, s59, s83
	s_mov_b32 m0, s38
	ds_read_b128 v[214:217], v167 offset:16384
	ds_read_b128 v[218:221], v167 offset:17408
	ds_read_b128 v[222:225], v167 offset:18432
	ds_read_b128 v[226:229], v167 offset:19456
	ds_read_b128 v[230:233], v167 offset:20480
	ds_read_b128 v[234:237], v167 offset:21504
	ds_read_b128 v[238:241], v167 offset:22528
	ds_read_b128 v[242:245], v167 offset:23552
	global_load_lds_dwordx4 v134, s[74:75]
	s_add_i32 m0, s38, 0x2000
	s_add_u32 s38, s74, 0x40000
	s_addc_u32 s39, s75, 0
	s_add_i32 s51, s51, s83
	global_load_lds_dwordx4 v130, s[74:75]
	s_mov_b32 m0, s51
	s_nop 0
	global_load_lds_dwordx4 v134, s[38:39]
	s_add_i32 m0, s51, 0x2000
	s_nop 0
	global_load_lds_dwordx4 v130, s[38:39]
	s_mov_b32 m0, s84
	s_nop 0
	global_load_lds_dwordx4 v136, s[76:77]
	s_mov_b32 m0, s85
	s_nop 0
	global_load_lds_dwordx4 v132, s[76:77]
	s_waitcnt vmcnt(8)
	s_waitcnt lgkmcnt(0)
	s_setprio 1
	s_barrier
	v_mfma_f32_16x16x32_bf16 v[62:65], v[170:173], v[214:217], v[62:65]
	v_mfma_f32_16x16x32_bf16 v[58:61], v[178:181], v[214:217], v[58:61]
	v_mfma_f32_16x16x32_bf16 v[46:49], v[170:173], v[222:225], v[46:49]
	v_mfma_f32_16x16x32_bf16 v[42:45], v[178:181], v[222:225], v[42:45]
	v_mfma_f32_16x16x32_bf16 v[30:33], v[170:173], v[230:233], v[30:33]
	v_mfma_f32_16x16x32_bf16 v[26:29], v[178:181], v[230:233], v[26:29]
	v_mfma_f32_16x16x32_bf16 v[14:17], v[170:173], v[238:241], v[14:17]
	v_mfma_f32_16x16x32_bf16 v[10:13], v[178:181], v[238:241], v[10:13]
	v_mfma_f32_16x16x32_bf16 v[62:65], v[174:177], v[218:221], v[62:65]
	v_mfma_f32_16x16x32_bf16 v[58:61], v[182:185], v[218:221], v[58:61]
	v_mfma_f32_16x16x32_bf16 v[46:49], v[174:177], v[226:229], v[46:49]
	v_mfma_f32_16x16x32_bf16 v[42:45], v[182:185], v[226:229], v[42:45]
	v_mfma_f32_16x16x32_bf16 v[30:33], v[174:177], v[234:237], v[30:33]
	v_mfma_f32_16x16x32_bf16 v[26:29], v[182:185], v[234:237], v[26:29]
	v_mfma_f32_16x16x32_bf16 v[14:17], v[174:177], v[242:245], v[14:17]
	v_mfma_f32_16x16x32_bf16 v[10:13], v[182:185], v[242:245], v[10:13]
	v_mfma_f32_16x16x32_bf16 v[54:57], v[186:189], v[214:217], v[54:57]
	v_mfma_f32_16x16x32_bf16 v[50:53], v[206:209], v[214:217], v[50:53]
	v_mfma_f32_16x16x32_bf16 v[38:41], v[186:189], v[222:225], v[38:41]
	v_mfma_f32_16x16x32_bf16 v[34:37], v[206:209], v[222:225], v[34:37]
	v_mfma_f32_16x16x32_bf16 v[22:25], v[186:189], v[230:233], v[22:25]
	v_mfma_f32_16x16x32_bf16 v[18:21], v[206:209], v[230:233], v[18:21]
	v_mfma_f32_16x16x32_bf16 v[6:9], v[186:189], v[238:241], v[6:9]
	v_mfma_f32_16x16x32_bf16 v[2:5], v[206:209], v[238:241], v[2:5]
	v_mfma_f32_16x16x32_bf16 v[54:57], v[190:193], v[218:221], v[54:57]
	v_mfma_f32_16x16x32_bf16 v[50:53], v[210:213], v[218:221], v[50:53]
	v_mfma_f32_16x16x32_bf16 v[38:41], v[190:193], v[226:229], v[38:41]
	v_mfma_f32_16x16x32_bf16 v[34:37], v[210:213], v[226:229], v[34:37]
	v_mfma_f32_16x16x32_bf16 v[22:25], v[190:193], v[234:237], v[22:25]
	v_mfma_f32_16x16x32_bf16 v[18:21], v[210:213], v[234:237], v[18:21]
	v_mfma_f32_16x16x32_bf16 v[6:9], v[190:193], v[242:245], v[6:9]
	v_mfma_f32_16x16x32_bf16 v[2:5], v[210:213], v[242:245], v[2:5]
	s_setprio 0
	s_barrier
; #define PG8_STAGE(bufoff, gbase, voff) do { _Pragma("unroll") for (int _i = 0; _i < 2; ++_i) \
;         __builtin_amdgcn_global_load_lds((const unsigned*)((const char*)(gbase) + (voff)[_i]), (PG8_LAS unsigned*)(lds + (bufoff) + ldsw + _i * 8192), 16, 0, 0); } while (0)
; #define PG8_LDA(dst, b, h) do { _Pragma("unroll") for (int m = 0; m < 4; ++m) _Pragma("unroll") for (int k = 0; k < 2; ++k) dst[m][k] = *(const PG8_LAS bf16x8*)(lds + PG8_SA(b, h) + aoff + m * 2048 + k * 1024); } while (0)
; #define PG8_LDB(dst, b, h) do { _Pragma("unroll") for (int n = 0; n < 2; ++n) _Pragma("unroll") for (int k = 0; k < 2; ++k) dst[n][k] = *(const PG8_LAS bf16x8*)(lds + PG8_SB(b, h) + boff + n * 2048 + k * 1024); } while (0)
; #define PG8_MMA(ai, bj, At, Bt) do { __builtin_amdgcn_s_setprio(1); _Pragma("unroll") for (int m = 0; m < 4; ++m) _Pragma("unroll") for (int n = 0; n < 2; ++n) _Pragma("unroll") for (int k = 0; k < 2; ++k) \
;         acc[ai][bj][m][n] = __builtin_amdgcn_mfma_f32_16x16x32_bf16(Bt[n][k], At[m][k], acc[ai][bj][m][n], 0, 0, 0); __builtin_amdgcn_s_setprio(0); } while (0)
; #define PG8_WAIT_V(n) asm volatile("s_waitcnt vmcnt(" #n ")" ::: "memory")
; #define PG8_WAIT_L(n) asm volatile("s_waitcnt lgkmcnt(" #n ")" ::: "memory")
; #define PG8_BAR __builtin_amdgcn_s_barrier()
; #define PG8_SCHED __builtin_amdgcn_sched_barrier(0)
; template <class Epi, class Sched, bool ALIGN_EPI = false, bool SP2 = false>
; __device__ __forceinline__ void gemm_phase(PG8_LAS unsigned char* lds, const Gemm g, const Sched& S, const Epi& E, const int tid) {
;     ...
;             PG8_LDB(B0, 1, 0); PG8_LDB(B1, 1, 1); PG8_SCHED; PG8_LDA(At, 1, 0); PG8_STAGE(PG8_SA(0, 1), a2 + hstep, voffA);
;             PG8_WAIT_V(8); PG8_WAIT_L(0); PG8_BAR; PG8_MMA(0, 0, At, B0); PG8_MMA(0, 1, At, B1); PG8_BAR; PG8_SCHED;
;             PG8_LDA(At, 1, 1); PG8_STAGE(PG8_SB(1, 0), b3, voffB); PG8_STAGE(PG8_SB(1, 1), b3 + hstep, voffB); PG8_STAGE(PG8_SA(1, 0), a3, voffA);
;             PG8_WAIT_V(8); PG8_WAIT_L(0); PG8_BAR; PG8_MMA(1, 0, At, B0); PG8_MMA(1, 1, At, B1); PG8_BAR; PG8_SCHED;
	s_add_i32 s51, 0, 0x18000
	s_add_i32 s59, 0, 0x1c000
	ds_read_b128 v[170:173], v0 offset:32768
	ds_read_b128 v[174:177], v0 offset:33792
	ds_read_b128 v[178:181], v0 offset:34816
	ds_read_b128 v[182:185], v0 offset:35840
	ds_read_b128 v[186:189], v0 offset:49152
	ds_read_b128 v[190:193], v0 offset:50176
	ds_read_b128 v[206:209], v0 offset:51200
	ds_read_b128 v[210:213], v0 offset:52224
	s_add_u32 s38, s76, 0x40000
	s_addc_u32 s39, s77, 0
	s_mov_b32 m0, s86
	ds_read_b128 v[214:217], v167 offset:32768
	ds_read_b128 v[218:221], v167 offset:33792
	ds_read_b128 v[222:225], v167 offset:34816
	ds_read_b128 v[226:229], v167 offset:35840
	ds_read_b128 v[230:233], v167 offset:36864
	ds_read_b128 v[234:237], v167 offset:37888
	ds_read_b128 v[238:241], v167 offset:38912
	ds_read_b128 v[242:245], v167 offset:39936
	global_load_lds_dwordx4 v136, s[38:39]
	s_mov_b32 m0, s87
	s_nop 0
	global_load_lds_dwordx4 v132, s[38:39]
	s_waitcnt vmcnt(8)
	s_waitcnt lgkmcnt(0)
	s_setprio 1
	s_barrier
	v_mfma_f32_16x16x32_bf16 v[126:129], v[170:173], v[214:217], v[126:129]
	v_mfma_f32_16x16x32_bf16 v[122:125], v[178:181], v[214:217], v[122:125]
	v_mfma_f32_16x16x32_bf16 v[110:113], v[170:173], v[222:225], v[110:113]
	v_mfma_f32_16x16x32_bf16 v[106:109], v[178:181], v[222:225], v[106:109]
	v_mfma_f32_16x16x32_bf16 v[94:97], v[170:173], v[230:233], v[94:97]
	v_mfma_f32_16x16x32_bf16 v[90:93], v[178:181], v[230:233], v[90:93]
	v_mfma_f32_16x16x32_bf16 v[78:81], v[170:173], v[238:241], v[78:81]
	v_mfma_f32_16x16x32_bf16 v[74:77], v[178:181], v[238:241], v[74:77]
	v_mfma_f32_16x16x32_bf16 v[126:129], v[174:177], v[218:221], v[126:129]
	v_mfma_f32_16x16x32_bf16 v[122:125], v[182:185], v[218:221], v[122:125]
	v_mfma_f32_16x16x32_bf16 v[110:113], v[174:177], v[226:229], v[110:113]
	v_mfma_f32_16x16x32_bf16 v[106:109], v[182:185], v[226:229], v[106:109]
	v_mfma_f32_16x16x32_bf16 v[94:97], v[174:177], v[234:237], v[94:97]
	v_mfma_f32_16x16x32_bf16 v[90:93], v[182:185], v[234:237], v[90:93]
	v_mfma_f32_16x16x32_bf16 v[78:81], v[174:177], v[242:245], v[78:81]
	v_mfma_f32_16x16x32_bf16 v[74:77], v[182:185], v[242:245], v[74:77]
	v_mfma_f32_16x16x32_bf16 v[118:121], v[186:189], v[214:217], v[118:121]
	v_mfma_f32_16x16x32_bf16 v[114:117], v[206:209], v[214:217], v[114:117]
	v_mfma_f32_16x16x32_bf16 v[102:105], v[186:189], v[222:225], v[102:105]
	v_mfma_f32_16x16x32_bf16 v[98:101], v[206:209], v[222:225], v[98:101]
	v_mfma_f32_16x16x32_bf16 v[86:89], v[186:189], v[230:233], v[86:89]
	v_mfma_f32_16x16x32_bf16 v[82:85], v[206:209], v[230:233], v[82:85]
	v_mfma_f32_16x16x32_bf16 v[70:73], v[186:189], v[238:241], v[70:73]
	v_mfma_f32_16x16x32_bf16 v[66:69], v[206:209], v[238:241], v[66:69]
	v_mfma_f32_16x16x32_bf16 v[118:121], v[190:193], v[218:221], v[118:121]
	v_mfma_f32_16x16x32_bf16 v[114:117], v[210:213], v[218:221], v[114:117]
	v_mfma_f32_16x16x32_bf16 v[102:105], v[190:193], v[226:229], v[102:105]
	v_mfma_f32_16x16x32_bf16 v[98:101], v[210:213], v[226:229], v[98:101]
	v_mfma_f32_16x16x32_bf16 v[86:89], v[190:193], v[234:237], v[86:89]
	v_mfma_f32_16x16x32_bf16 v[82:85], v[210:213], v[234:237], v[82:85]
	v_mfma_f32_16x16x32_bf16 v[70:73], v[190:193], v[242:245], v[70:73]
	v_mfma_f32_16x16x32_bf16 v[66:69], v[210:213], v[242:245], v[66:69]
	s_setprio 0
	s_barrier
	s_add_i32 s38, s51, s83
	s_add_i32 m0, s38, 0xffffff80
	ds_read_b128 v[214:217], v167 offset:49152
	ds_read_b128 v[218:221], v167 offset:50176
	ds_read_b128 v[222:225], v167 offset:51200
	ds_read_b128 v[226:229], v167 offset:52224
	ds_read_b128 v[230:233], v167 offset:53248
	ds_read_b128 v[234:237], v167 offset:54272
	ds_read_b128 v[238:241], v167 offset:55296
	ds_read_b128 v[242:245], v167 offset:56320
	global_load_lds_dwordx4 v134, s[74:75] offset:128
	s_add_i32 m0, s38, 0x1f80
	s_add_u32 s38, s74, 0x40080
	s_addc_u32 s39, s75, 0
	s_add_i32 s51, s59, s83
	global_load_lds_dwordx4 v130, s[74:75] offset:128
	s_mov_b32 m0, s51
	s_nop 0
	global_load_lds_dwordx4 v134, s[38:39]
	s_add_i32 m0, s51, 0x2000
	s_nop 0
	global_load_lds_dwordx4 v130, s[38:39]
	s_add_i32 m0, s88, 0xffffff80
	s_nop 0
	global_load_lds_dwordx4 v136, s[76:77] offset:128
	s_add_i32 m0, s89, 0xffffff80
	s_nop 0
	global_load_lds_dwordx4 v132, s[76:77] offset:128
	s_waitcnt vmcnt(8)
	s_waitcnt lgkmcnt(0)
	s_setprio 1
	s_barrier
	v_mfma_f32_16x16x32_bf16 v[62:65], v[170:173], v[214:217], v[62:65]
	v_mfma_f32_16x16x32_bf16 v[58:61], v[178:181], v[214:217], v[58:61]
	v_mfma_f32_16x16x32_bf16 v[46:49], v[170:173], v[222:225], v[46:49]
	v_mfma_f32_16x16x32_bf16 v[42:45], v[178:181], v[222:225], v[42:45]
	v_mfma_f32_16x16x32_bf16 v[30:33], v[170:173], v[230:233], v[30:33]
	v_mfma_f32_16x16x32_bf16 v[26:29], v[178:181], v[230:233], v[26:29]
	v_mfma_f32_16x16x32_bf16 v[14:17], v[170:173], v[238:241], v[14:17]
	v_mfma_f32_16x16x32_bf16 v[10:13], v[178:181], v[238:241], v[10:13]
	v_mfma_f32_16x16x32_bf16 v[62:65], v[174:177], v[218:221], v[62:65]
	v_mfma_f32_16x16x32_bf16 v[58:61], v[182:185], v[218:221], v[58:61]
	v_mfma_f32_16x16x32_bf16 v[46:49], v[174:177], v[226:229], v[46:49]
	v_mfma_f32_16x16x32_bf16 v[42:45], v[182:185], v[226:229], v[42:45]
	v_mfma_f32_16x16x32_bf16 v[30:33], v[174:177], v[234:237], v[30:33]
	v_mfma_f32_16x16x32_bf16 v[26:29], v[182:185], v[234:237], v[26:29]
	v_mfma_f32_16x16x32_bf16 v[14:17], v[174:177], v[242:245], v[14:17]
	v_mfma_f32_16x16x32_bf16 v[10:13], v[182:185], v[242:245], v[10:13]
	v_mfma_f32_16x16x32_bf16 v[54:57], v[186:189], v[214:217], v[54:57]
	v_mfma_f32_16x16x32_bf16 v[50:53], v[206:209], v[214:217], v[50:53]
	v_mfma_f32_16x16x32_bf16 v[38:41], v[186:189], v[222:225], v[38:41]
	v_mfma_f32_16x16x32_bf16 v[34:37], v[206:209], v[222:225], v[34:37]
	v_mfma_f32_16x16x32_bf16 v[22:25], v[186:189], v[230:233], v[22:25]
	v_mfma_f32_16x16x32_bf16 v[18:21], v[206:209], v[230:233], v[18:21]
	v_mfma_f32_16x16x32_bf16 v[6:9], v[186:189], v[238:241], v[6:9]
	v_mfma_f32_16x16x32_bf16 v[2:5], v[206:209], v[238:241], v[2:5]
	v_mfma_f32_16x16x32_bf16 v[54:57], v[190:193], v[218:221], v[54:57]
	v_mfma_f32_16x16x32_bf16 v[50:53], v[210:213], v[218:221], v[50:53]
	v_mfma_f32_16x16x32_bf16 v[38:41], v[190:193], v[226:229], v[38:41]
	v_mfma_f32_16x16x32_bf16 v[34:37], v[210:213], v[226:229], v[34:37]
	v_mfma_f32_16x16x32_bf16 v[22:25], v[190:193], v[234:237], v[22:25]
	v_mfma_f32_16x16x32_bf16 v[18:21], v[210:213], v[234:237], v[18:21]
	v_mfma_f32_16x16x32_bf16 v[6:9], v[190:193], v[242:245], v[6:9]
	v_mfma_f32_16x16x32_bf16 v[2:5], v[210:213], v[242:245], v[2:5]
	s_setprio 0
	s_barrier
	s_add_i32 s50, s50, 2
	s_add_u32 s12, s12, 0x100
	s_addc_u32 s13, s13, 0
	s_cmp_gt_u32 s50, 13
	s_cbranch_scc1 .LBB0_211
